# CW: counted LDS waits in the PV sections - staging ds_write issued after the next V-fragment read, and lgkmcnt raised so the MFMA wait covers only the fragment read, not the staging store
# speedup vs baseline: 1.0029x; 1.0029x over previous
.LBB0_672:
	s_nop 7
	v_exp_f32_e32 v2, v48
	v_exp_f32_e32 v3, v49
	v_exp_f32_e32 v4, v50
	v_exp_f32_e32 v5, v51
	v_add_f32_e32 v0, 0, v2
	v_exp_f32_e32 v6, v52
	v_add_f32_e32 v0, v3, v0
	v_exp_f32_e32 v7, v53
	v_add_f32_e32 v0, v4, v0
	v_exp_f32_e32 v8, v54
	v_add_f32_e32 v0, v5, v0
	v_exp_f32_e32 v9, v55
	v_add_f32_e32 v0, v6, v0
	v_add_f32_e32 v0, v7, v0
	v_exp_f32_e32 v50, v60
	v_exp_f32_e32 v60, v70
	v_add3_u32 v70, s6, v143, v145
	v_add_f32_e32 v0, v8, v0
	v_exp_f32_e32 v51, v61
	v_exp_f32_e32 v61, v71
	v_add_u32_e32 v71, 0x2000, v70
	v_add_f32_e32 v0, v9, v0
	v_cvt_pk_bf16_f32 v2, v2, v3
	v_cvt_pk_bf16_f32 v3, v4, v5
	v_cvt_pk_bf16_f32 v4, v6, v7
	v_cvt_pk_bf16_f32 v5, v8, v9
	ds_read2_b64 v[6:9], v71 offset0:128 offset1:130
	ds_read2_b64 v[10:13], v71 offset0:132 offset1:134
	v_add_u32_e32 v70, 0x3000, v70
	s_waitcnt lgkmcnt(1)
	v_mfma_f32_32x32x16_bf16 v[32:47], v[6:9], v[2:5], v[32:47]
	ds_read2_b64 v[6:9], v70 offset0:160 offset1:162
	s_mul_i32 s16, s4, 0x4a00
	v_or_b32_e32 v252, s16, v125
	v_add_u32_e32 v253, v252, v137
	s_waitcnt vmcnt(3)
	ds_write_b128 v253, v[100:103]
	global_load_dwordx4 v[100:103], v228, s[10:11]
	v_exp_f32_e32 v14, v56
	v_exp_f32_e32 v15, v57
	v_exp_f32_e32 v48, v58
	v_exp_f32_e32 v49, v59
	v_exp_f32_e32 v52, v62
	v_exp_f32_e32 v53, v63
	s_waitcnt lgkmcnt(1)
	v_mfma_f32_32x32x16_bf16 v[16:31], v[6:9], v[2:5], v[16:31]
	ds_read2_b64 v[6:9], v70 offset0:164 offset1:166
	v_add3_u32 v253, v252, v138, s33
	s_waitcnt vmcnt(2)
	ds_write2_b64 v253, v[104:105], v[106:107] offset1:1
	global_load_dwordx4 v[104:107], v230, s[22:23]
	v_cvt_pk_bf16_f32 v2, v14, v15
	v_cvt_pk_bf16_f32 v3, v48, v49
	v_cvt_pk_bf16_f32 v4, v50, v51
	v_cvt_pk_bf16_f32 v5, v52, v53
	v_exp_f32_e32 v54, v64
	v_exp_f32_e32 v55, v65
	s_waitcnt lgkmcnt(1)
	v_mfma_f32_32x32x16_bf16 v[16:31], v[6:9], v[2:5], v[16:31]
	ds_read2_b64 v[6:9], v71 offset0:136 offset1:138
	v_add_u32_e32 v253, v252, v139
	s_waitcnt vmcnt(3)
	ds_write_b128 v253, v[108:111]
	global_load_dwordx4 v[108:111], v229, s[10:11]
	v_exp_f32_e32 v56, v66
	v_exp_f32_e32 v57, v67
	v_exp_f32_e32 v58, v68
	v_exp_f32_e32 v59, v69
	v_add_f32_e32 v0, v14, v0
	v_add_f32_e32 v0, v15, v0
	v_mfma_f32_32x32x16_bf16 v[32:47], v[10:13], v[2:5], v[32:47]
	v_add3_u32 v253, v252, v140, s33
	s_waitcnt vmcnt(3)
	ds_write2_b64 v253, v[112:113], v[114:115] offset1:1
	global_load_dwordx4 v[112:115], v231, s[22:23]
	s_add_u32 s10, s10, 0x2000
	s_addc_u32 s11, s11, 0
	s_add_u32 s22, s22, 0x80
	s_addc_u32 s23, s23, 0
	v_cvt_pk_bf16_f32 v2, v54, v55
	v_cvt_pk_bf16_f32 v3, v56, v57
	v_cvt_pk_bf16_f32 v4, v58, v59
	v_cvt_pk_bf16_f32 v5, v60, v61
	v_add_f32_e32 v0, v48, v0
	v_add_f32_e32 v0, v49, v0
	v_exp_f32_e32 v62, v72
	s_waitcnt lgkmcnt(2)
	v_mfma_f32_32x32x16_bf16 v[32:47], v[6:9], v[2:5], v[32:47]
	ds_read2_b64 v[6:9], v70 offset0:168 offset1:170
	v_exp_f32_e32 v63, v73
	v_exp_f32_e32 v64, v74
	v_exp_f32_e32 v65, v75
	v_exp_f32_e32 v66, v76
	v_exp_f32_e32 v67, v77
	v_exp_f32_e32 v68, v78
	s_waitcnt lgkmcnt(0)
	v_mfma_f32_32x32x16_bf16 v[16:31], v[6:9], v[2:5], v[16:31]
	ds_read2_b64 v[6:9], v71 offset0:140 offset1:142
	v_exp_f32_e32 v69, v79
	v_add_f32_e32 v0, v50, v0
	v_add_f32_e32 v0, v51, v0
	v_add_f32_e32 v0, v52, v0
	v_add_f32_e32 v0, v53, v0
	v_cvt_pk_bf16_f32 v2, v62, v63
	v_cvt_pk_bf16_f32 v3, v64, v65
	v_cvt_pk_bf16_f32 v4, v66, v67
	v_cvt_pk_bf16_f32 v5, v68, v69
	v_add_f32_e32 v0, v54, v0
	v_add_f32_e32 v0, v55, v0
	s_waitcnt lgkmcnt(0)
	v_mfma_f32_32x32x16_bf16 v[32:47], v[6:9], v[2:5], v[32:47]
	ds_read2_b64 v[6:9], v70 offset0:172 offset1:174
	v_add_f32_e32 v0, v56, v0
	v_add_f32_e32 v0, v57, v0
	v_add_f32_e32 v0, v58, v0
	v_add_f32_e32 v0, v59, v0
	v_add_f32_e32 v0, v60, v0
	v_add_f32_e32 v0, v61, v0
	v_add_f32_e32 v0, v62, v0
	v_add_f32_e32 v0, v63, v0
	s_waitcnt lgkmcnt(0)
	v_mfma_f32_32x32x16_bf16 v[16:31], v[6:9], v[2:5], v[16:31]
	s_and_saveexec_b64 s[0:1], s[38:39]
	s_cbranch_execz .Ld5f_noga
	s_waitcnt vmcnt(4)
	v_xor_b32_e32 v239, 0x80000000, v99
	v_xor_b32_e32 v238, 0x80000000, v98
	v_xor_b32_e32 v237, 0x80000000, v97
	v_xor_b32_e32 v236, 0x80000000, v96
	v_add_u32_e32 v253, s16, v119
	ds_write_b128 v253, v[236:239] offset:18432
	global_load_dwordx4 v[96:99], v228, s[24:25]

.LBB0_705:
	s_nop 7
	v_exp_f32_e32 v2, v80
	v_exp_f32_e32 v3, v81
	v_exp_f32_e32 v4, v82
	v_exp_f32_e32 v5, v83
	v_add_f32_e32 v0, 0, v2
	v_exp_f32_e32 v6, v84
	v_add_f32_e32 v0, v3, v0
	v_exp_f32_e32 v7, v85
	v_add_f32_e32 v0, v4, v0
	v_exp_f32_e32 v8, v86
	v_add_f32_e32 v0, v5, v0
	v_exp_f32_e32 v9, v87
	v_add_f32_e32 v0, v6, v0
	v_add_f32_e32 v0, v7, v0
	v_add3_u32 v86, s14, v147, v149
	v_add_f32_e32 v0, v8, v0
	v_add_u32_e32 v87, 0x2000, v86
	v_add_f32_e32 v0, v9, v0
	v_cvt_pk_bf16_f32 v2, v2, v3
	v_cvt_pk_bf16_f32 v3, v4, v5
	v_cvt_pk_bf16_f32 v4, v6, v7
	v_cvt_pk_bf16_f32 v5, v8, v9
	ds_read2_b64 v[6:9], v87 offset0:128 offset1:130
	ds_read2_b64 v[10:13], v87 offset0:132 offset1:134
	v_add_u32_e32 v86, 0x3000, v86
	s_waitcnt lgkmcnt(1)
	v_mfma_f32_32x32x16_bf16 v[32:47], v[6:9], v[2:5], v[32:47]
	ds_read2_b64 v[6:9], v86 offset0:160 offset1:162
	s_mul_i32 s1, s9, 0x4a00
	v_or_b32_e32 v184, s1, v131
	v_add_u32_e32 v185, v184, v133
	s_waitcnt vmcnt(3)
	ds_write_b128 v185, v[108:111]
	global_load_dwordx4 v[108:111], v180, s[10:11]
	v_exp_f32_e32 v14, v88
	v_exp_f32_e32 v15, v89
	v_exp_f32_e32 v80, v90
	v_exp_f32_e32 v81, v91
	v_exp_f32_e32 v82, v92
	v_exp_f32_e32 v83, v93
	s_waitcnt lgkmcnt(1)
	v_mfma_f32_32x32x16_bf16 v[16:31], v[6:9], v[2:5], v[16:31]
	ds_read2_b64 v[6:9], v86 offset0:164 offset1:166
	v_add3_u32 v185, v184, v144, s33
	s_waitcnt vmcnt(2)
	ds_write2_b64 v185, v[104:105], v[106:107] offset1:1
	global_load_dwordx4 v[104:107], v182, s[16:17]
	v_exp_f32_e32 v84, v94
	v_exp_f32_e32 v85, v95
	v_cvt_pk_bf16_f32 v2, v14, v15
	v_cvt_pk_bf16_f32 v3, v80, v81
	v_cvt_pk_bf16_f32 v4, v82, v83
	v_cvt_pk_bf16_f32 v5, v84, v85
	v_exp_f32_e32 v64, v64
	v_exp_f32_e32 v65, v65
	s_waitcnt lgkmcnt(1)
	v_mfma_f32_32x32x16_bf16 v[16:31], v[6:9], v[2:5], v[16:31]
	ds_read2_b64 v[6:9], v87 offset0:136 offset1:138
	v_add_u32_e32 v185, v184, v145
	s_waitcnt vmcnt(3)
	ds_write_b128 v185, v[112:115]
	global_load_dwordx4 v[112:115], v181, s[10:11]
	v_exp_f32_e32 v66, v66
	v_exp_f32_e32 v67, v67
	v_exp_f32_e32 v68, v68
	v_exp_f32_e32 v69, v69
	v_exp_f32_e32 v70, v70
	v_exp_f32_e32 v71, v71
	v_mfma_f32_32x32x16_bf16 v[32:47], v[10:13], v[2:5], v[32:47]
	v_add3_u32 v185, v184, v146, s33
	s_waitcnt vmcnt(3)
	ds_write2_b64 v185, v[116:117], v[118:119] offset1:1
	global_load_dwordx4 v[116:119], v183, s[16:17]
	s_add_u32 s10, s10, 0x2000
	s_addc_u32 s11, s11, 0
	s_add_u32 s16, s16, 0x80
	s_addc_u32 s17, s17, 0
	v_cvt_pk_bf16_f32 v2, v64, v65
	v_cvt_pk_bf16_f32 v3, v66, v67
	v_cvt_pk_bf16_f32 v4, v68, v69
	v_cvt_pk_bf16_f32 v5, v70, v71
	v_add_f32_e32 v0, v14, v0
	v_add_f32_e32 v0, v15, v0
	v_add_f32_e32 v0, v80, v0
	s_waitcnt lgkmcnt(2)
	v_mfma_f32_32x32x16_bf16 v[32:47], v[6:9], v[2:5], v[32:47]
	ds_read2_b64 v[6:9], v86 offset0:168 offset1:170
	v_add_f32_e32 v0, v81, v0
	v_exp_f32_e32 v72, v72
	v_exp_f32_e32 v73, v73
	v_exp_f32_e32 v74, v74
	v_exp_f32_e32 v75, v75
	v_exp_f32_e32 v76, v76
	s_waitcnt lgkmcnt(0)
	v_mfma_f32_32x32x16_bf16 v[16:31], v[6:9], v[2:5], v[16:31]
	ds_read2_b64 v[6:9], v87 offset0:140 offset1:142
	v_exp_f32_e32 v77, v77
	v_exp_f32_e32 v78, v78
	v_exp_f32_e32 v79, v79
	v_add_f32_e32 v0, v82, v0
	v_add_f32_e32 v0, v83, v0
	v_add_f32_e32 v0, v84, v0
	v_add_f32_e32 v0, v85, v0
	v_cvt_pk_bf16_f32 v2, v72, v73
	v_cvt_pk_bf16_f32 v3, v74, v75
	v_cvt_pk_bf16_f32 v4, v76, v77
	v_cvt_pk_bf16_f32 v5, v78, v79
	v_add_f32_e32 v0, v64, v0
	v_add_f32_e32 v0, v65, v0
	s_waitcnt lgkmcnt(0)
	v_mfma_f32_32x32x16_bf16 v[32:47], v[6:9], v[2:5], v[32:47]
	ds_read2_b64 v[6:9], v86 offset0:172 offset1:174
	v_add_f32_e32 v0, v66, v0
	v_add_f32_e32 v0, v67, v0
	v_add_f32_e32 v0, v68, v0
	v_add_f32_e32 v0, v69, v0
	v_add_f32_e32 v0, v70, v0
	v_add_f32_e32 v0, v71, v0
	v_add_f32_e32 v0, v72, v0
	v_add_f32_e32 v0, v73, v0
	s_waitcnt lgkmcnt(0)
	v_mfma_f32_32x32x16_bf16 v[16:31], v[6:9], v[2:5], v[16:31]
	v_add_f32_e32 v0, v74, v0
	v_add_f32_e32 v0, v75, v0
	v_add_f32_e32 v0, v76, v0
	v_add_f32_e32 v0, v77, v0
	v_add_f32_e32 v0, v78, v0
	v_add_f32_e32 v0, v79, v0
	v_add_f32_e32 v152, v152, v0
	v_cmp_lt_f32_e32 vcc, s20, v0
	s_cbranch_vccz .LBB0_707
	v_mov_b32_e32 v2, v0
	s_nop 1
	v_permlane32_swap_b32_e32 v0, v2
	v_add_f32_e32 v0, v0, v2
	v_log_f32_e32 v2, v0
	v_cmp_lt_f32_e32 vcc, s20, v0
	s_nop 1
	v_cndmask_b32_e32 v2, 0, v2, vcc
	v_exp_f32_e64 v0, -v2
	v_add_f32_e32 v153, v153, v2
	v_xor_b32_e32 v63, 0x80000000, v153
	v_mov_b32_e32 v62, v63
	v_mul_f32_e32 v152, v152, v0
	v_pk_mul_f32 v[46:47], v[46:47], v[0:1] op_sel_hi:[1,0]
	v_pk_mul_f32 v[44:45], v[44:45], v[0:1] op_sel_hi:[1,0]
	v_pk_mul_f32 v[42:43], v[42:43], v[0:1] op_sel_hi:[1,0]
	v_pk_mul_f32 v[40:41], v[40:41], v[0:1] op_sel_hi:[1,0]
	v_pk_mul_f32 v[38:39], v[38:39], v[0:1] op_sel_hi:[1,0]
	v_pk_mul_f32 v[36:37], v[36:37], v[0:1] op_sel_hi:[1,0]
	v_pk_mul_f32 v[34:35], v[34:35], v[0:1] op_sel_hi:[1,0]
	v_pk_mul_f32 v[32:33], v[32:33], v[0:1] op_sel_hi:[1,0]
	v_pk_mul_f32 v[30:31], v[30:31], v[0:1] op_sel_hi:[1,0]
	v_pk_mul_f32 v[28:29], v[28:29], v[0:1] op_sel_hi:[1,0]
	v_pk_mul_f32 v[26:27], v[26:27], v[0:1] op_sel_hi:[1,0]
	v_pk_mul_f32 v[24:25], v[24:25], v[0:1] op_sel_hi:[1,0]
	v_pk_mul_f32 v[22:23], v[22:23], v[0:1] op_sel_hi:[1,0]
	v_pk_mul_f32 v[20:21], v[20:21], v[0:1] op_sel_hi:[1,0]
	v_pk_mul_f32 v[18:19], v[18:19], v[0:1] op_sel_hi:[1,0]
	v_pk_mul_f32 v[16:17], v[16:17], v[0:1] op_sel_hi:[1,0]
	v_mov_b32_e32 v61, v63
	v_mov_b32_e32 v60, v63
	v_mov_b32_e32 v59, v63
	v_mov_b32_e32 v58, v63
	v_mov_b32_e32 v57, v63
	v_mov_b32_e32 v56, v63
	v_mov_b32_e32 v55, v63
	v_mov_b32_e32 v54, v63
	v_mov_b32_e32 v53, v63
	v_mov_b32_e32 v52, v63
	v_mov_b32_e32 v51, v63
	v_mov_b32_e32 v50, v63
	v_mov_b32_e32 v49, v63
	v_mov_b32_e32 v48, v63
	s_branch .LBB0_707

.LBB0_919:
	s_nop 7
	v_exp_f32_e32 v66, v66
	v_exp_f32_e32 v67, v67
	v_exp_f32_e32 v68, v68
	v_exp_f32_e32 v69, v69
	v_add_f32_e32 v147, 0, v66
	v_exp_f32_e32 v70, v70
	v_add_f32_e32 v147, v67, v147
	v_exp_f32_e32 v71, v71
	v_add_f32_e32 v147, v68, v147
	v_exp_f32_e32 v72, v72
	v_add_f32_e32 v147, v69, v147
	v_exp_f32_e32 v73, v73
	v_add_f32_e32 v147, v70, v147
	v_exp_f32_e32 v74, v74
	v_add_f32_e32 v147, v71, v147
	v_exp_f32_e32 v75, v75
	v_add_f32_e32 v147, v72, v147
	v_exp_f32_e32 v76, v76
	v_add_f32_e32 v147, v73, v147
	v_exp_f32_e32 v77, v77
	v_add_f32_e32 v147, v74, v147
	v_exp_f32_e32 v78, v78
	v_add_f32_e32 v147, v75, v147
	v_exp_f32_e32 v79, v79
	v_add_f32_e32 v147, v76, v147
	v_exp_f32_e32 v80, v80
	v_add_f32_e32 v147, v77, v147
	v_exp_f32_e32 v81, v81
	v_add_f32_e32 v147, v78, v147
	v_exp_f32_e32 v148, v50
	v_add_f32_e32 v147, v79, v147
	v_exp_f32_e32 v149, v51
	v_add_f32_e32 v50, v80, v147
	v_add_f32_e32 v50, v81, v50
	v_add3_u32 v153, s22, v181, v187
	v_add_f32_e32 v50, v148, v50
	v_add_u32_e32 v154, 0x2000, v153
	v_add_f32_e32 v147, v149, v50
	v_exp_f32_e32 v150, v52
	v_exp_f32_e32 v151, v53
	ds_read2_b64 v[50:53], v154 offset0:128 offset1:130
	v_add_u32_e32 v153, 0x3000, v153
	v_exp_f32_e32 v152, v54
	v_cvt_pk_bf16_f32 v54, v66, v67
	v_cvt_pk_bf16_f32 v66, v68, v69
	v_cvt_pk_bf16_f32 v67, v70, v71
	v_cvt_pk_bf16_f32 v68, v72, v73
	ds_read2_b64 v[70:73], v153 offset0:160 offset1:162
	v_cndmask_b32_e64 v69, 0, v68, s[0:1]
	v_cndmask_b32_e64 v68, 0, v67, s[0:1]
	v_cndmask_b32_e64 v67, 0, v66, s[0:1]
	v_cndmask_b32_e64 v66, 0, v54, s[0:1]
	v_exp_f32_e32 v155, v55
	v_exp_f32_e32 v193, v56
	s_waitcnt lgkmcnt(1)
	v_mfma_f32_32x32x16_bf16 v[18:33], v[50:53], v[66:69], v[18:33]
	s_mul_i32 s23, s17, 0x4a00
	v_or_b32_e32 v252, s23, v129
	v_add_u32_e32 v253, v252, v131
	s_waitcnt vmcnt(3)
	ds_write_b128 v253, v[98:101]
	global_load_dwordx4 v[98:101], v228, s[12:13]
	v_add_f32_e32 v50, v150, v147
	v_add_f32_e32 v50, v151, v50
	v_add_f32_e32 v147, v152, v50
	ds_read2_b64 v[50:53], v154 offset0:132 offset1:134
	v_exp_f32_e32 v194, v57
	v_cvt_pk_bf16_f32 v54, v74, v75
	v_cvt_pk_bf16_f32 v55, v76, v77
	s_waitcnt lgkmcnt(2)
	v_mfma_f32_32x32x16_bf16 v[2:17], v[70:73], v[66:69], v[2:17]
	ds_read2_b64 v[66:69], v153 offset0:164 offset1:166
	v_add3_u32 v253, v252, v185, s33
	s_waitcnt vmcnt(2)
	ds_write2_b64 v253, v[102:103], v[104:105] offset1:1
	global_load_dwordx4 v[102:105], v230, s[24:25]
	v_cvt_pk_bf16_f32 v56, v78, v79
	v_cvt_pk_bf16_f32 v57, v80, v81
	v_cndmask_b32_e64 v57, 0, v57, s[0:1]
	v_cndmask_b32_e64 v56, 0, v56, s[0:1]
	v_cndmask_b32_e64 v55, 0, v55, s[0:1]
	v_cndmask_b32_e64 v54, 0, v54, s[0:1]
	v_exp_f32_e32 v58, v58
	v_exp_f32_e32 v59, v59
	s_waitcnt lgkmcnt(2)
	v_mfma_f32_32x32x16_bf16 v[18:33], v[50:53], v[54:57], v[18:33]
	v_add_u32_e32 v253, v252, v180
	s_waitcnt vmcnt(3)
	ds_write_b128 v253, v[106:109]
	global_load_dwordx4 v[106:109], v229, s[12:13]
	v_add_f32_e32 v50, v155, v147
	v_add_f32_e32 v50, v193, v50
	v_add_f32_e32 v50, v194, v50
	v_add_f32_e32 v70, v58, v50
	ds_read2_b64 v[50:53], v154 offset0:136 offset1:138
	v_exp_f32_e32 v60, v60
	v_exp_f32_e32 v71, v61
	s_waitcnt lgkmcnt(3)
	v_mfma_f32_32x32x16_bf16 v[2:17], v[66:69], v[54:57], v[2:17]
	ds_read2_b64 v[66:69], v153 offset0:168 offset1:170
	v_add3_u32 v253, v252, v186, s33
	s_waitcnt vmcnt(3)
	ds_write2_b64 v253, v[110:111], v[112:113] offset1:1
	global_load_dwordx4 v[110:113], v231, s[24:25]
	s_add_u32 s12, s12, 0x2000
	s_addc_u32 s13, s13, 0
	s_add_u32 s24, s24, 0x80
	s_addc_u32 s25, s25, 0
	v_cvt_pk_bf16_f32 v54, v148, v149
	v_cvt_pk_bf16_f32 v55, v150, v151
	v_cvt_pk_bf16_f32 v56, v152, v155
	v_cvt_pk_bf16_f32 v57, v193, v194
	v_cndmask_b32_e64 v57, 0, v57, s[0:1]
	v_cndmask_b32_e64 v56, 0, v56, s[0:1]
	v_cndmask_b32_e64 v55, 0, v55, s[0:1]
	v_cndmask_b32_e64 v54, 0, v54, s[0:1]
	v_exp_f32_e32 v62, v62
	v_exp_f32_e32 v63, v63
	s_waitcnt lgkmcnt(2)
	v_mfma_f32_32x32x16_bf16 v[18:33], v[50:53], v[54:57], v[18:33]
	v_add_f32_e32 v50, v59, v70
	v_add_f32_e32 v70, v60, v50
	ds_read2_b64 v[50:53], v154 offset0:140 offset1:142
	v_exp_f32_e32 v64, v64
	v_exp_f32_e32 v65, v65
	s_waitcnt lgkmcnt(2)
	v_mfma_f32_32x32x16_bf16 v[2:17], v[66:69], v[54:57], v[2:17]
	v_cvt_pk_bf16_f32 v54, v58, v59
	v_cvt_pk_bf16_f32 v55, v60, v71
	ds_read2_b64 v[58:61], v153 offset0:172 offset1:174
	v_cvt_pk_bf16_f32 v56, v62, v63
	v_cvt_pk_bf16_f32 v57, v64, v65
	v_cndmask_b32_e64 v57, 0, v57, s[0:1]
	v_cndmask_b32_e64 v56, 0, v56, s[0:1]
	v_cndmask_b32_e64 v55, 0, v55, s[0:1]
	v_cndmask_b32_e64 v54, 0, v54, s[0:1]
	s_waitcnt lgkmcnt(1)
	s_nop 0
	v_mfma_f32_32x32x16_bf16 v[18:33], v[50:53], v[54:57], v[18:33]
	v_add_f32_e32 v50, v71, v70
	v_add_f32_e32 v50, v62, v50
	v_add_f32_e32 v50, v63, v50
	v_add_f32_e32 v50, v64, v50
	v_add_f32_e32 v50, v65, v50
	v_cndmask_b32_e64 v50, 0, v50, s[0:1]
	v_add_f32_e32 v133, v133, v50
	s_waitcnt lgkmcnt(0)
	v_mfma_f32_32x32x16_bf16 v[2:17], v[58:61], v[54:57], v[2:17]
	v_cmp_lt_f32_e32 vcc, s20, v50
	s_cbranch_vccz .LBB0_921
	v_mov_b32_e32 v34, v50
	s_nop 1
	v_permlane32_swap_b32_e32 v50, v34
	v_add_f32_e32 v34, v50, v34
	v_log_f32_e32 v35, v34
	v_cmp_lt_f32_e32 vcc, s20, v34
	s_nop 1
	v_cndmask_b32_e32 v35, 0, v35, vcc
	v_exp_f32_e64 v34, -v35
	v_add_f32_e32 v135, v135, v35
	v_xor_b32_e32 v49, 0x80000000, v135
	v_mov_b32_e32 v48, v49
	v_mul_f32_e32 v133, v133, v34
	v_pk_mul_f32 v[32:33], v[32:33], v[34:35] op_sel_hi:[1,0]
	v_pk_mul_f32 v[30:31], v[30:31], v[34:35] op_sel_hi:[1,0]
	v_pk_mul_f32 v[28:29], v[28:29], v[34:35] op_sel_hi:[1,0]
	v_pk_mul_f32 v[26:27], v[26:27], v[34:35] op_sel_hi:[1,0]
	v_pk_mul_f32 v[24:25], v[24:25], v[34:35] op_sel_hi:[1,0]
	v_pk_mul_f32 v[22:23], v[22:23], v[34:35] op_sel_hi:[1,0]
	v_pk_mul_f32 v[20:21], v[20:21], v[34:35] op_sel_hi:[1,0]
	v_pk_mul_f32 v[18:19], v[18:19], v[34:35] op_sel_hi:[1,0]
	v_pk_mul_f32 v[16:17], v[16:17], v[34:35] op_sel_hi:[1,0]
	v_pk_mul_f32 v[14:15], v[14:15], v[34:35] op_sel_hi:[1,0]
	v_pk_mul_f32 v[12:13], v[12:13], v[34:35] op_sel_hi:[1,0]
	v_pk_mul_f32 v[10:11], v[10:11], v[34:35] op_sel_hi:[1,0]
	v_pk_mul_f32 v[8:9], v[8:9], v[34:35] op_sel_hi:[1,0]
	v_pk_mul_f32 v[6:7], v[6:7], v[34:35] op_sel_hi:[1,0]
	v_pk_mul_f32 v[4:5], v[4:5], v[34:35] op_sel_hi:[1,0]
	v_pk_mul_f32 v[2:3], v[2:3], v[34:35] op_sel_hi:[1,0]
	v_mov_b32_e32 v47, v49
	v_mov_b32_e32 v46, v49
	v_mov_b32_e32 v45, v49
	v_mov_b32_e32 v44, v49
	v_mov_b32_e32 v43, v49
	v_mov_b32_e32 v42, v49
	v_mov_b32_e32 v41, v49
	v_mov_b32_e32 v40, v49
	v_mov_b32_e32 v39, v49
	v_mov_b32_e32 v38, v49
	v_mov_b32_e32 v37, v49
	v_mov_b32_e32 v36, v49
	v_mov_b32_e32 v35, v49
	v_mov_b32_e32 v34, v49
	s_branch .LBB0_921

.LBB0_936:
	s_nop 4
	v_exp_f32_e32 v66, v66
	v_exp_f32_e32 v67, v67
	v_exp_f32_e32 v68, v68
	v_exp_f32_e32 v69, v69
	v_add_f32_e32 v138, 0, v66
	v_exp_f32_e32 v70, v70
	v_add_f32_e32 v138, v67, v138
	v_exp_f32_e32 v71, v71
	v_add_f32_e32 v138, v68, v138
	v_exp_f32_e32 v72, v72
	v_add_f32_e32 v138, v69, v138
	v_exp_f32_e32 v73, v73
	v_add_f32_e32 v138, v70, v138
	v_exp_f32_e32 v74, v74
	v_add_f32_e32 v138, v71, v138
	v_exp_f32_e32 v75, v75
	v_add_f32_e32 v138, v72, v138
	v_exp_f32_e32 v76, v76
	v_add_f32_e32 v138, v73, v138
	v_exp_f32_e32 v77, v77
	v_add_f32_e32 v138, v74, v138
	v_exp_f32_e32 v78, v78
	v_add_f32_e32 v138, v75, v138
	v_exp_f32_e32 v79, v79
	v_add_f32_e32 v138, v76, v138
	v_exp_f32_e32 v80, v80
	v_add_f32_e32 v138, v77, v138
	v_exp_f32_e32 v81, v81
	v_add_f32_e32 v138, v78, v138
	v_exp_f32_e32 v139, v50
	v_add_f32_e32 v138, v79, v138
	v_add_f32_e32 v138, v80, v138
	v_add_f32_e32 v138, v81, v138
	v_add_f32_e32 v50, v139, v138
	v_exp_f32_e32 v138, v52
	v_cvt_pk_bf16_f32 v52, v66, v67
	v_add3_u32 v66, s16, v181, v187
	v_add_u32_e32 v67, 0x2000, v66
	v_exp_f32_e32 v143, v56
	v_exp_f32_e32 v144, v57
	v_exp_f32_e32 v145, v58
	v_exp_f32_e32 v147, v59
	v_exp_f32_e32 v148, v60
	v_exp_f32_e32 v149, v61
	v_exp_f32_e32 v150, v62
	v_exp_f32_e32 v151, v63
	ds_read2_b64 v[56:59], v67 offset0:128 offset1:130
	ds_read2_b64 v[60:63], v67 offset0:132 offset1:134
	v_exp_f32_e32 v140, v53
	v_exp_f32_e32 v141, v54
	v_exp_f32_e32 v142, v55
	v_cvt_pk_bf16_f32 v53, v68, v69
	v_cvt_pk_bf16_f32 v54, v70, v71
	v_cvt_pk_bf16_f32 v55, v72, v73
	v_add_u32_e32 v66, 0x3000, v66
	v_exp_f32_e32 v51, v51
	s_waitcnt lgkmcnt(1)
	v_mfma_f32_32x32x16_bf16 v[18:33], v[56:59], v[52:55], v[18:33]
	ds_read2_b64 v[56:59], v66 offset0:160 offset1:162
	s_mul_i32 s22, s15, 0x4a00
	v_or_b32_e32 v252, s22, v129
	v_add_u32_e32 v253, v252, v131
	s_waitcnt vmcnt(3)
	ds_write_b128 v253, v[98:101]
	global_load_dwordx4 v[98:101], v228, s[12:13]
	v_exp_f32_e32 v64, v64
	v_exp_f32_e32 v65, v65
	v_add_f32_e32 v50, v51, v50
	v_add_f32_e32 v50, v138, v50
	v_add_f32_e32 v50, v140, v50
	v_add_f32_e32 v50, v141, v50
	s_waitcnt lgkmcnt(1)
	v_mfma_f32_32x32x16_bf16 v[2:17], v[56:59], v[52:55], v[2:17]
	ds_read2_b64 v[56:59], v66 offset0:164 offset1:166
	v_add3_u32 v253, v252, v185, s33
	s_waitcnt vmcnt(2)
	ds_write2_b64 v253, v[102:103], v[104:105] offset1:1
	global_load_dwordx4 v[102:105], v230, s[24:25]
	v_cvt_pk_bf16_f32 v52, v74, v75
	v_cvt_pk_bf16_f32 v53, v76, v77
	v_cvt_pk_bf16_f32 v54, v78, v79
	v_cvt_pk_bf16_f32 v55, v80, v81
	v_add_f32_e32 v50, v142, v50
	v_add_f32_e32 v50, v143, v50
	s_waitcnt lgkmcnt(1)
	v_mfma_f32_32x32x16_bf16 v[2:17], v[56:59], v[52:55], v[2:17]
	ds_read2_b64 v[56:59], v67 offset0:136 offset1:138
	v_add_u32_e32 v253, v252, v180
	s_waitcnt vmcnt(3)
	ds_write_b128 v253, v[106:109]
	global_load_dwordx4 v[106:109], v229, s[12:13]
	v_add_f32_e32 v50, v144, v50
	v_add_f32_e32 v50, v145, v50
	v_add_f32_e32 v50, v147, v50
	v_add_f32_e32 v50, v148, v50
	v_add_f32_e32 v50, v149, v50
	v_add_f32_e32 v50, v150, v50
	v_mfma_f32_32x32x16_bf16 v[18:33], v[60:63], v[52:55], v[18:33]
	v_add3_u32 v253, v252, v186, s33
	s_waitcnt vmcnt(3)
	ds_write2_b64 v253, v[110:111], v[112:113] offset1:1
	global_load_dwordx4 v[110:113], v231, s[24:25]
	s_add_u32 s12, s12, 0x2000
	s_addc_u32 s13, s13, 0
	s_add_u32 s24, s24, 0x80
	s_addc_u32 s25, s25, 0
	v_cvt_pk_bf16_f32 v52, v139, v51
	v_cvt_pk_bf16_f32 v53, v138, v140
	v_cvt_pk_bf16_f32 v54, v141, v142
	v_cvt_pk_bf16_f32 v55, v143, v144
	v_add_f32_e32 v50, v151, v50
	v_add_f32_e32 v50, v64, v50
	v_add_f32_e32 v50, v65, v50
	s_waitcnt lgkmcnt(2)
	v_mfma_f32_32x32x16_bf16 v[18:33], v[56:59], v[52:55], v[18:33]
	ds_read2_b64 v[56:59], v66 offset0:168 offset1:170
	v_add_f32_e32 v136, v136, v50
	v_cmp_lt_f32_e32 vcc, s20, v50
	s_waitcnt lgkmcnt(0)
	v_mfma_f32_32x32x16_bf16 v[2:17], v[56:59], v[52:55], v[2:17]
	ds_read2_b64 v[56:59], v67 offset0:140 offset1:142
	v_cvt_pk_bf16_f32 v52, v145, v147
	v_cvt_pk_bf16_f32 v53, v148, v149
	v_cvt_pk_bf16_f32 v54, v150, v151
	v_cvt_pk_bf16_f32 v55, v64, v65
	s_waitcnt lgkmcnt(0)
	s_nop 0
	v_mfma_f32_32x32x16_bf16 v[18:33], v[56:59], v[52:55], v[18:33]
	ds_read2_b64 v[56:59], v66 offset0:172 offset1:174
	s_waitcnt lgkmcnt(0)
	v_mfma_f32_32x32x16_bf16 v[2:17], v[56:59], v[52:55], v[2:17]
	s_cbranch_vccz .LBB0_938
	v_mov_b32_e32 v34, v50
	s_nop 1
	v_permlane32_swap_b32_e32 v50, v34
	v_add_f32_e32 v34, v50, v34
	v_log_f32_e32 v35, v34
	v_cmp_lt_f32_e32 vcc, s20, v34
	s_nop 1
	v_cndmask_b32_e32 v35, 0, v35, vcc
	v_exp_f32_e64 v34, -v35
	v_add_f32_e32 v0, v0, v35
	v_xor_b32_e32 v49, 0x80000000, v0
	v_mov_b32_e32 v48, v49
	v_mul_f32_e32 v136, v136, v34
	v_pk_mul_f32 v[32:33], v[32:33], v[34:35] op_sel_hi:[1,0]
	v_pk_mul_f32 v[30:31], v[30:31], v[34:35] op_sel_hi:[1,0]
	v_pk_mul_f32 v[28:29], v[28:29], v[34:35] op_sel_hi:[1,0]
	v_pk_mul_f32 v[26:27], v[26:27], v[34:35] op_sel_hi:[1,0]
	v_pk_mul_f32 v[24:25], v[24:25], v[34:35] op_sel_hi:[1,0]
	v_pk_mul_f32 v[22:23], v[22:23], v[34:35] op_sel_hi:[1,0]
	v_pk_mul_f32 v[20:21], v[20:21], v[34:35] op_sel_hi:[1,0]
	v_pk_mul_f32 v[18:19], v[18:19], v[34:35] op_sel_hi:[1,0]
	v_pk_mul_f32 v[16:17], v[16:17], v[34:35] op_sel_hi:[1,0]
	v_pk_mul_f32 v[14:15], v[14:15], v[34:35] op_sel_hi:[1,0]
	v_pk_mul_f32 v[12:13], v[12:13], v[34:35] op_sel_hi:[1,0]
	v_pk_mul_f32 v[10:11], v[10:11], v[34:35] op_sel_hi:[1,0]
	v_pk_mul_f32 v[8:9], v[8:9], v[34:35] op_sel_hi:[1,0]
	v_pk_mul_f32 v[6:7], v[6:7], v[34:35] op_sel_hi:[1,0]
	v_pk_mul_f32 v[4:5], v[4:5], v[34:35] op_sel_hi:[1,0]
	v_pk_mul_f32 v[2:3], v[2:3], v[34:35] op_sel_hi:[1,0]
	v_mov_b32_e32 v47, v49
	v_mov_b32_e32 v46, v49
	v_mov_b32_e32 v45, v49
	v_mov_b32_e32 v44, v49
	v_mov_b32_e32 v43, v49
	v_mov_b32_e32 v42, v49
	v_mov_b32_e32 v41, v49
	v_mov_b32_e32 v40, v49
	v_mov_b32_e32 v39, v49
	v_mov_b32_e32 v38, v49
	v_mov_b32_e32 v37, v49
	v_mov_b32_e32 v36, v49
	v_mov_b32_e32 v35, v49
	v_mov_b32_e32 v34, v49
	s_branch .LBB0_938
